# FFN-in x4: SwiGLU output stores carry the streaming (nt) cache policy
# speedup vs baseline: 1.0025x; 1.0025x over previous
; __device__ __forceinline__ unsigned cvt_pk_bf16(float lo, float hi) { unsigned r; asm volatile("v_cvt_pk_bf16_f32 %0, %1, %2" : "=v"(r) : "v"(lo), "v"(hi)); return r; }
;     __device__ __forceinline__ void half(const f32x4 (&acc)[2][4][2], int pm, int ai, int pn, int wr, int wc, int fr, int fq) const {
;     ...
;             for (int m = 0; m < 4; ++m) {
;                 float a[8], e[8];
; #pragma unroll
;                 for (int q = 0; q < 8; ++q) a[q] = acc[0][m][q >> 2][q & 3];
; #pragma unroll
;                 for (int q = 0; q < 8; ++q) e[q] = __builtin_amdgcn_exp2f(-a[q]);
; #pragma unroll
;                 for (int q = 0; q < 8; ++q) e[q] += 1.f;
; #pragma unroll
;                 for (int q = 0; q < 8; ++q) e[q] = __builtin_amdgcn_rcpf(e[q]);
; #pragma unroll
;                 for (int q = 0; q < 8; ++q) a[q] = a[q] * acc[1][m][q >> 2][q & 3] * e[q];
;                 u32x4 w; w.x = cvt_pk_bf16(a[0], a[1]); w.y = cvt_pk_bf16(a[2], a[3]); w.z = cvt_pk_bf16(a[4], a[5]); w.w = cvt_pk_bf16(a[6], a[7]);
;                 const int row = row0 + ai * HALF + m * 16;
;                 bf16_t* dst = O + (((size_t)(row >> 8) * (ldc >> 6) + (col0 >> 6)) * 256 + (row & 255)) * 64 + (col0 & 63);
;                 if (wt) asm volatile("global_store_dwordx4 %0, %1, off sc1\n\ts_nop 1" :: "v"(dst), "v"(w) : "memory"); else *(u32x4*)dst = w; }
.LBB0_303:
	v_exp_f32_e64 v159, -v120
	v_exp_f32_e64 v160, -v121
	v_exp_f32_e64 v155, -v124
	v_exp_f32_e64 v156, -v125
	v_exp_f32_e64 v157, -v126
	v_exp_f32_e64 v161, -v122
	v_exp_f32_e64 v158, -v127
	v_exp_f32_e64 v162, -v123
	s_lshl_b32 s4, s54, 8
	v_add_f32_e32 v159, 1.0, v159
	s_lshl_b32 s5, s52, 7
	s_add_i32 s12, s4, s11
	v_add_f32_e32 v160, 1.0, v160
	v_rcp_f32_e32 v159, v159
	s_or_b32 s5, s5, s33
	s_ashr_i32 s12, s12, 8
	v_add_f32_e32 v155, 1.0, v155
	v_add_f32_e32 v156, 1.0, v156
	v_add_f32_e32 v157, 1.0, v157
	v_add_f32_e32 v161, 1.0, v161
	v_rcp_f32_e32 v160, v160
	s_ashr_i32 s50, s5, 6
	v_add_f32_e32 v158, 1.0, v158
	v_add_f32_e32 v162, 1.0, v162
	v_rcp_f32_e32 v155, v155
	v_rcp_f32_e32 v156, v156
	v_rcp_f32_e32 v157, v157
	v_rcp_f32_e32 v161, v161
	s_mulk_i32 s12, 0x58
	s_ashr_i32 s51, s50, 31
	v_rcp_f32_e32 v158, v158
	v_rcp_f32_e32 v162, v162
	v_mul_f32_e32 v112, v112, v120
	s_ashr_i32 s5, s12, 31
	v_mul_f32_e32 v120, v112, v159
	v_mul_f32_e32 v112, v113, v121
	s_add_u32 s12, s12, s50
	v_mul_f32_e32 v116, v116, v124
	v_mul_f32_e32 v117, v117, v125
	v_mul_f32_e32 v118, v118, v126
	v_mul_f32_e32 v121, v112, v160
	v_mul_f32_e32 v112, v114, v122
	s_addc_u32 s13, s5, s51
	v_mul_f32_e32 v116, v116, v155
	v_mul_f32_e32 v117, v117, v156
	v_mul_f32_e32 v118, v118, v157
	v_mul_f32_e32 v119, v119, v127
	v_mul_f32_e32 v122, v112, v161
	v_mul_f32_e32 v112, v115, v123
	s_lshl_b64 s[12:13], s[12:13], 15
	v_mul_f32_e32 v119, v119, v158
	v_mul_f32_e32 v115, v112, v162
	v_cvt_pk_bf16_f32 v112, v116, v117
	v_cvt_pk_bf16_f32 v113, v118, v119
	v_lshl_add_u64 v[116:117], v[138:139], 0, s[12:13]
	v_exp_f32_e64 v118, -v104
	v_lshl_add_u64 v[116:117], v[116:117], 0, v[136:137]
	v_exp_f32_e64 v119, -v105
	v_cvt_pk_bf16_f32 v114, v120, v121
	v_cvt_pk_bf16_f32 v115, v122, v115
	global_store_dwordx4 v[116:117], v[112:115], off nt
	v_exp_f32_e64 v120, -v106
	v_exp_f32_e64 v121, -v107
	v_exp_f32_e64 v112, -v108
	v_exp_f32_e64 v113, -v109
	v_exp_f32_e64 v114, -v110
	v_exp_f32_e64 v115, -v111
	v_add_f32_e32 v118, 1.0, v118
	v_add_f32_e32 v119, 1.0, v119
	v_rcp_f32_e32 v118, v118
	v_add_f32_e32 v112, 1.0, v112
	v_add_f32_e32 v120, 1.0, v120
	v_rcp_f32_e32 v119, v119
	v_add_f32_e32 v113, 1.0, v113
	v_add_f32_e32 v121, 1.0, v121
	v_rcp_f32_e32 v112, v112
	v_rcp_f32_e32 v120, v120
	v_add_f32_e32 v114, 1.0, v114
	v_add_f32_e32 v115, 1.0, v115
	v_rcp_f32_e32 v113, v113
	v_rcp_f32_e32 v121, v121
	v_mul_f32_e32 v96, v96, v104
	v_rcp_f32_e32 v114, v114
	v_rcp_f32_e32 v115, v115
	v_mul_f32_e32 v104, v96, v118
	v_mul_f32_e32 v96, v97, v105
	v_mul_f32_e32 v100, v100, v108
	v_mul_f32_e32 v105, v96, v119
	v_mul_f32_e32 v96, v98, v106
	v_mul_f32_e32 v100, v100, v112
	v_mul_f32_e32 v101, v101, v109
	v_mul_f32_e32 v106, v96, v120
	v_mul_f32_e32 v96, v99, v107
	v_mul_f32_e32 v101, v101, v113
	v_mul_f32_e32 v102, v102, v110
	v_mul_f32_e32 v103, v103, v111
	v_mul_f32_e32 v99, v96, v121
	v_cvt_pk_bf16_f32 v96, v100, v101
	v_exp_f32_e64 v100, -v88
	v_mul_f32_e32 v102, v102, v114
	v_mul_f32_e32 v103, v103, v115
	v_cvt_pk_bf16_f32 v97, v102, v103
	v_cvt_pk_bf16_f32 v98, v104, v105
	v_exp_f32_e64 v101, -v89
	v_cvt_pk_bf16_f32 v99, v106, v99
	global_store_dwordx4 v[116:117], v[96:99], off offset:2048 nt
	v_exp_f32_e64 v102, -v90
	v_exp_f32_e64 v103, -v91
	v_exp_f32_e64 v96, -v92
	v_exp_f32_e64 v98, -v94
	v_exp_f32_e64 v97, -v93
	v_exp_f32_e64 v99, -v95
	v_add_f32_e32 v100, 1.0, v100
	v_add_f32_e32 v101, 1.0, v101
	v_rcp_f32_e32 v100, v100
	v_add_f32_e32 v96, 1.0, v96
	v_add_f32_e32 v98, 1.0, v98
	v_add_f32_e32 v102, 1.0, v102
	v_rcp_f32_e32 v101, v101
	v_add_f32_e32 v97, 1.0, v97
	v_add_f32_e32 v99, 1.0, v99
	v_add_f32_e32 v103, 1.0, v103
	v_rcp_f32_e32 v96, v96
	v_rcp_f32_e32 v98, v98
	v_rcp_f32_e32 v102, v102
	v_rcp_f32_e32 v97, v97
	v_rcp_f32_e32 v99, v99
	v_rcp_f32_e32 v103, v103
	v_mul_f32_e32 v80, v80, v88
	v_mul_f32_e32 v88, v80, v100
	v_mul_f32_e32 v80, v81, v89
	v_mul_f32_e32 v84, v84, v92
	v_mul_f32_e32 v86, v86, v94
	v_mul_f32_e32 v89, v80, v101
	v_mul_f32_e32 v80, v82, v90
	v_mul_f32_e32 v84, v84, v96
	v_mul_f32_e32 v85, v85, v93
	v_mul_f32_e32 v86, v86, v98
	v_mul_f32_e32 v87, v87, v95
	v_mul_f32_e32 v90, v80, v102
	v_mul_f32_e32 v80, v83, v91
	v_mul_f32_e32 v85, v85, v97
	v_mul_f32_e32 v87, v87, v99
	v_mul_f32_e32 v83, v80, v103
	v_cvt_pk_bf16_f32 v80, v84, v85
	v_cvt_pk_bf16_f32 v81, v86, v87
	v_add_co_u32_e32 v84, vcc, s60, v116
	v_exp_f32_e64 v86, -v72
	s_nop 0
	v_addc_co_u32_e32 v85, vcc, 0, v117, vcc
	v_exp_f32_e64 v87, -v73
	v_cvt_pk_bf16_f32 v82, v88, v89
	v_cvt_pk_bf16_f32 v83, v90, v83
	global_store_dwordx4 v[84:85], v[80:83], off nt
	v_exp_f32_e64 v88, -v74
	v_exp_f32_e64 v89, -v75
	v_exp_f32_e64 v81, -v77
	v_exp_f32_e64 v80, -v76
	v_exp_f32_e64 v82, -v78
	v_exp_f32_e64 v83, -v79
	v_add_f32_e32 v86, 1.0, v86
	v_add_f32_e32 v87, 1.0, v87
	v_rcp_f32_e32 v86, v86
	v_add_f32_e32 v81, 1.0, v81
	v_add_f32_e32 v88, 1.0, v88
	v_rcp_f32_e32 v87, v87
	v_add_f32_e32 v80, 1.0, v80
	v_add_f32_e32 v82, 1.0, v82
	v_add_f32_e32 v89, 1.0, v89
	v_rcp_f32_e32 v81, v81
	v_rcp_f32_e32 v88, v88
	v_add_f32_e32 v83, 1.0, v83
	v_rcp_f32_e32 v80, v80
	v_rcp_f32_e32 v82, v82
	v_rcp_f32_e32 v89, v89
	v_mul_f32_e32 v64, v64, v72
	v_rcp_f32_e32 v83, v83
	v_mul_f32_e32 v72, v64, v86
	v_mul_f32_e32 v64, v65, v73
	v_mul_f32_e32 v69, v69, v77
	v_mul_f32_e32 v73, v64, v87
	v_mul_f32_e32 v64, v66, v74
	v_mul_f32_e32 v68, v68, v76
	v_mul_f32_e32 v69, v69, v81
	v_mul_f32_e32 v70, v70, v78
	v_mul_f32_e32 v74, v64, v88
	v_mul_f32_e32 v64, v67, v75
	v_mul_f32_e32 v68, v68, v80
	v_mul_f32_e32 v70, v70, v82
	v_mul_f32_e32 v71, v71, v79
	v_mul_f32_e32 v67, v64, v89
	v_cvt_pk_bf16_f32 v64, v68, v69
; __device__ __forceinline__ unsigned cvt_pk_bf16(float lo, float hi) { unsigned r; asm volatile("v_cvt_pk_bf16_f32 %0, %1, %2" : "=v"(r) : "v"(lo), "v"(hi)); return r; }
; #define PG8_BAR __builtin_amdgcn_s_barrier()
;     __device__ __forceinline__ void half(const f32x4 (&acc)[2][4][2], int pm, int ai, int pn, int wr, int wc, int fr, int fq) const {
;     ...
;             for (int m = 0; m < 4; ++m) {
;                 float a[8], e[8];
; #pragma unroll
;                 for (int q = 0; q < 8; ++q) a[q] = acc[0][m][q >> 2][q & 3];
; #pragma unroll
;                 for (int q = 0; q < 8; ++q) e[q] = __builtin_amdgcn_exp2f(-a[q]);
; #pragma unroll
;                 for (int q = 0; q < 8; ++q) e[q] += 1.f;
; #pragma unroll
;                 for (int q = 0; q < 8; ++q) e[q] = __builtin_amdgcn_rcpf(e[q]);
; #pragma unroll
;                 for (int q = 0; q < 8; ++q) a[q] = a[q] * acc[1][m][q >> 2][q & 3] * e[q];
;                 u32x4 w; w.x = cvt_pk_bf16(a[0], a[1]); w.y = cvt_pk_bf16(a[2], a[3]); w.z = cvt_pk_bf16(a[4], a[5]); w.w = cvt_pk_bf16(a[6], a[7]);
;                 const int row = row0 + ai * HALF + m * 16;
;                 bf16_t* dst = O + (((size_t)(row >> 8) * (ldc >> 6) + (col0 >> 6)) * 256 + (row & 255)) * 64 + (col0 & 63);
;                 if (wt) asm volatile("global_store_dwordx4 %0, %1, off sc1\n\ts_nop 1" :: "v"(dst), "v"(w) : "memory"); else *(u32x4*)dst = w; }
; template <class Epi, class Sched, bool ALIGN_EPI = false, bool SP2 = false>
; __device__ __forceinline__ void gemm_phase(PG8_LAS unsigned char* lds, const Gemm g, const Sched& S, const Epi& E) {
;     ...
;         if (!has_next) break;
; #pragma unroll
;         for (int a = 0; a < 2; ++a)
; #pragma unroll
;             for (int b = 0; b < 2; ++b)
; #pragma unroll
;                 for (int m = 0; m < 4; ++m)
; #pragma unroll
;                     for (int n = 0; n < 2; ++n) acc[a][b][m][n] = (f32x4){0.f, 0.f, 0.f, 0.f};
;         cur = nxt; cA = nA; cB = nB; ++ui;
;         if constexpr (ALIGN_EPI) { if (wr == 1) PG8_BAR; }
	v_exp_f32_e64 v69, -v56
	v_mul_f32_e32 v71, v71, v83
	v_cvt_pk_bf16_f32 v65, v70, v71
	v_exp_f32_e64 v70, -v57
	v_cvt_pk_bf16_f32 v66, v72, v73
	v_cvt_pk_bf16_f32 v67, v74, v67
	global_store_dwordx4 v[84:85], v[64:67], off offset:2048 nt
	v_exp_f32_e64 v71, -v58
	v_exp_f32_e64 v72, -v59
	v_exp_f32_e64 v65, -v60
	v_exp_f32_e64 v66, -v61
	v_add_f32_e32 v69, 1.0, v69
	v_add_f32_e32 v70, 1.0, v70
	v_rcp_f32_e32 v69, v69
	v_exp_f32_e64 v67, -v62
	v_add_f32_e32 v65, 1.0, v65
	v_add_f32_e32 v71, 1.0, v71
	v_rcp_f32_e32 v70, v70
	v_exp_f32_e64 v68, -v63
	v_add_f32_e32 v66, 1.0, v66
	v_add_f32_e32 v72, 1.0, v72
	v_rcp_f32_e32 v65, v65
	v_rcp_f32_e32 v71, v71
	v_rcp_f32_e32 v66, v66
	v_rcp_f32_e32 v72, v72
	v_mul_f32_e32 v48, v48, v56
	v_mul_f32_e32 v56, v48, v69
	v_mul_f32_e32 v48, v49, v57
	v_add_u32_e32 v64, s4, v151
	v_add_f32_e32 v67, 1.0, v67
	v_mul_f32_e32 v52, v52, v60
	v_mul_f32_e32 v57, v48, v70
	v_mul_f32_e32 v48, v50, v58
	v_lshrrev_b32_e32 v64, 8, v64
	v_add_f32_e32 v68, 1.0, v68
	v_rcp_f32_e32 v67, v67
	v_mul_f32_e32 v52, v52, v65
	v_mul_f32_e32 v53, v53, v61
	v_mul_f32_e32 v58, v48, v71
	v_mul_f32_e32 v48, v51, v59
	v_rcp_f32_e32 v68, v68
	v_mul_f32_e32 v53, v53, v66
	v_mul_f32_e32 v51, v48, v72
	v_cvt_pk_bf16_f32 v48, v52, v53
	v_mul_i32_i24_e32 v52, 0x58, v64
	v_ashrrev_i32_e32 v53, 31, v52
	v_mul_f32_e32 v54, v54, v62
	v_lshl_add_u64 v[52:53], v[52:53], 0, s[50:51]
	v_mul_f32_e32 v54, v54, v67
	v_mul_f32_e32 v55, v55, v63
	v_lshlrev_b64 v[52:53], 15, v[52:53]
	v_mul_f32_e32 v55, v55, v68
	v_cvt_pk_bf16_f32 v49, v54, v55
	v_lshl_add_u64 v[52:53], v[140:141], 0, v[52:53]
	v_exp_f32_e64 v54, -v40
	v_lshl_add_u64 v[52:53], v[52:53], 0, v[136:137]
	v_exp_f32_e64 v55, -v41
	v_cvt_pk_bf16_f32 v50, v56, v57
	v_cvt_pk_bf16_f32 v51, v58, v51
	global_store_dwordx4 v[52:53], v[48:51], off nt
	v_exp_f32_e64 v56, -v42
	v_exp_f32_e64 v57, -v43
	v_exp_f32_e64 v48, -v44
	v_exp_f32_e64 v49, -v45
	v_exp_f32_e64 v50, -v46
	v_exp_f32_e64 v51, -v47
	v_add_f32_e32 v54, 1.0, v54
	v_add_f32_e32 v55, 1.0, v55
	v_rcp_f32_e32 v54, v54
	v_add_f32_e32 v48, 1.0, v48
	v_add_f32_e32 v56, 1.0, v56
	v_rcp_f32_e32 v55, v55
	v_add_f32_e32 v49, 1.0, v49
	v_add_f32_e32 v57, 1.0, v57
	v_rcp_f32_e32 v48, v48
	v_rcp_f32_e32 v56, v56
	v_add_f32_e32 v50, 1.0, v50
	v_add_f32_e32 v51, 1.0, v51
	v_rcp_f32_e32 v49, v49
	v_rcp_f32_e32 v57, v57
	v_mul_f32_e32 v32, v32, v40
	v_rcp_f32_e32 v50, v50
	v_rcp_f32_e32 v51, v51
	v_mul_f32_e32 v40, v32, v54
	v_mul_f32_e32 v32, v33, v41
	v_mul_f32_e32 v36, v36, v44
	v_mul_f32_e32 v41, v32, v55
	v_mul_f32_e32 v32, v34, v42
	v_mul_f32_e32 v36, v36, v48
	v_mul_f32_e32 v37, v37, v45
	v_mul_f32_e32 v42, v32, v56
	v_mul_f32_e32 v32, v35, v43
	v_mul_f32_e32 v37, v37, v49
	v_mul_f32_e32 v38, v38, v46
	v_mul_f32_e32 v39, v39, v47
	v_mul_f32_e32 v35, v32, v57
	v_cvt_pk_bf16_f32 v32, v36, v37
	v_exp_f32_e64 v36, -v24
	v_mul_f32_e32 v38, v38, v50
	v_mul_f32_e32 v39, v39, v51
	v_cvt_pk_bf16_f32 v33, v38, v39
	v_cvt_pk_bf16_f32 v34, v40, v41
	v_exp_f32_e64 v37, -v25
	v_cvt_pk_bf16_f32 v35, v42, v35
	global_store_dwordx4 v[52:53], v[32:35], off offset:2048 nt
	v_exp_f32_e64 v38, -v26
	v_exp_f32_e64 v39, -v27
	v_exp_f32_e64 v34, -v30
	v_exp_f32_e64 v32, -v28
	v_exp_f32_e64 v33, -v29
	v_exp_f32_e64 v35, -v31
	v_add_f32_e32 v36, 1.0, v36
	v_add_f32_e32 v37, 1.0, v37
	v_rcp_f32_e32 v36, v36
	v_add_f32_e32 v34, 1.0, v34
	v_add_f32_e32 v38, 1.0, v38
	v_rcp_f32_e32 v37, v37
	v_add_f32_e32 v32, 1.0, v32
	v_add_f32_e32 v33, 1.0, v33
	v_add_f32_e32 v35, 1.0, v35
	v_add_f32_e32 v39, 1.0, v39
	v_rcp_f32_e32 v34, v34
	v_rcp_f32_e32 v38, v38
	v_rcp_f32_e32 v32, v32
	v_rcp_f32_e32 v33, v33
	v_rcp_f32_e32 v35, v35
	v_rcp_f32_e32 v39, v39
	v_mul_f32_e32 v16, v16, v24
	v_mul_f32_e32 v24, v16, v36
	v_mul_f32_e32 v16, v17, v25
	v_mul_f32_e32 v22, v22, v30
	v_mul_f32_e32 v25, v16, v37
	v_mul_f32_e32 v16, v18, v26
	v_mul_f32_e32 v20, v20, v28
	v_mul_f32_e32 v21, v21, v29
	v_mul_f32_e32 v22, v22, v34
	v_mul_f32_e32 v23, v23, v31
	v_mul_f32_e32 v26, v16, v38
	v_mul_f32_e32 v16, v19, v27
	v_mul_f32_e32 v20, v20, v32
	v_mul_f32_e32 v21, v21, v33
	v_mul_f32_e32 v23, v23, v35
	v_mul_f32_e32 v19, v16, v39
	v_cvt_pk_bf16_f32 v16, v20, v21
	v_cvt_pk_bf16_f32 v17, v22, v23
	v_exp_f32_e64 v22, -v8
	v_exp_f32_e64 v23, -v9
	v_cvt_pk_bf16_f32 v18, v24, v25
	v_add_co_u32_e32 v20, vcc, s60, v52
	v_exp_f32_e64 v24, -v10
	v_cvt_pk_bf16_f32 v19, v26, v19
	s_nop 0
	v_addc_co_u32_e32 v21, vcc, 0, v53, vcc
	v_exp_f32_e64 v25, -v11
	global_store_dwordx4 v[20:21], v[16:19], off nt
	v_add_f32_e32 v22, 1.0, v22
	v_add_f32_e32 v23, 1.0, v23
	v_exp_f32_e64 v16, -v12
	v_exp_f32_e64 v17, -v13
	v_exp_f32_e64 v18, -v14
	v_exp_f32_e64 v19, -v15
	v_rcp_f32_e32 v22, v22
	v_add_f32_e32 v24, 1.0, v24
	v_rcp_f32_e32 v23, v23
	v_add_f32_e32 v25, 1.0, v25
	v_rcp_f32_e32 v24, v24
	v_add_f32_e32 v16, 1.0, v16
	v_add_f32_e32 v17, 1.0, v17
	v_add_f32_e32 v18, 1.0, v18
	v_add_f32_e32 v19, 1.0, v19
	v_rcp_f32_e32 v25, v25
	v_mul_f32_e32 v0, v0, v8
	v_rcp_f32_e32 v16, v16
	v_rcp_f32_e32 v17, v17
	v_rcp_f32_e32 v18, v18
	v_rcp_f32_e32 v19, v19
	v_mul_f32_e32 v8, v0, v22
	v_mul_f32_e32 v0, v1, v9
	v_mul_f32_e32 v9, v0, v23
	v_mul_f32_e32 v0, v2, v10
	v_mul_f32_e32 v10, v0, v24
	v_mul_f32_e32 v0, v3, v11
	v_mul_f32_e32 v4, v4, v12
	v_mul_f32_e32 v5, v5, v13
	v_mul_f32_e32 v6, v6, v14
	v_mul_f32_e32 v7, v7, v15
	v_mul_f32_e32 v3, v0, v25
	s_andn2_b64 vcc, exec, s[34:35]
	s_mov_b64 s[4:5], -1
	v_mul_f32_e32 v4, v4, v16
	v_mul_f32_e32 v5, v5, v17
	v_mul_f32_e32 v6, v6, v18
	v_mul_f32_e32 v7, v7, v19
	v_cvt_pk_bf16_f32 v0, v4, v5
	v_cvt_pk_bf16_f32 v1, v6, v7
	v_cvt_pk_bf16_f32 v2, v8, v9
	v_cvt_pk_bf16_f32 v3, v10, v3
	global_store_dwordx4 v[20:21], v[0:3], off offset:2048 nt
	s_cbranch_vccnz .LBB0_292
	s_andn2_b64 vcc, exec, s[0:1]
	s_cbranch_vccnz .LBB0_291
	s_barrier
	s_branch .LBB0_291

; __device__ __forceinline__ unsigned cvt_pk_bf16(float lo, float hi) { unsigned r; asm volatile("v_cvt_pk_bf16_f32 %0, %1, %2" : "=v"(r) : "v"(lo), "v"(hi)); return r; }
;     __device__ __forceinline__ void half(const f32x4 (&acc)[2][4][2], int pm, int ai, int pn, int wr, int wc, int fr, int fq) const {
;     ...
;             for (int m = 0; m < 4; ++m) {
;                 float a[8], e[8];
; #pragma unroll
;                 for (int q = 0; q < 8; ++q) a[q] = acc[0][m][q >> 2][q & 3];
; #pragma unroll
;                 for (int q = 0; q < 8; ++q) e[q] = __builtin_amdgcn_exp2f(-a[q]);
; #pragma unroll
;                 for (int q = 0; q < 8; ++q) e[q] += 1.f;
; #pragma unroll
;                 for (int q = 0; q < 8; ++q) e[q] = __builtin_amdgcn_rcpf(e[q]);
; #pragma unroll
;                 for (int q = 0; q < 8; ++q) a[q] = a[q] * acc[1][m][q >> 2][q & 3] * e[q];
;                 u32x4 w; w.x = cvt_pk_bf16(a[0], a[1]); w.y = cvt_pk_bf16(a[2], a[3]); w.z = cvt_pk_bf16(a[4], a[5]); w.w = cvt_pk_bf16(a[6], a[7]);
;                 const int row = row0 + ai * HALF + m * 16;
;                 bf16_t* dst = O + (((size_t)(row >> 8) * (ldc >> 6) + (col0 >> 6)) * 256 + (row & 255)) * 64 + (col0 & 63);
;                 if (wt) asm volatile("global_store_dwordx4 %0, %1, off sc1\n\ts_nop 1" :: "v"(dst), "v"(w) : "memory"); else *(u32x4*)dst = w; }
.LBB0_1310:
	v_exp_f32_e64 v159, -v120
	v_exp_f32_e64 v160, -v121
	v_exp_f32_e64 v155, -v124
	v_exp_f32_e64 v156, -v125
	v_exp_f32_e64 v157, -v126
	v_exp_f32_e64 v161, -v122
	v_exp_f32_e64 v158, -v127
	v_exp_f32_e64 v162, -v123
	s_lshl_b32 s4, s60, 8
	v_add_f32_e32 v159, 1.0, v159
	s_lshl_b32 s5, s54, 7
	s_add_i32 s12, s4, s46
	v_add_f32_e32 v160, 1.0, v160
	v_rcp_f32_e32 v159, v159
	s_or_b32 s5, s5, s47
	s_ashr_i32 s12, s12, 8
	v_add_f32_e32 v155, 1.0, v155
	v_add_f32_e32 v156, 1.0, v156
	v_add_f32_e32 v157, 1.0, v157
	v_add_f32_e32 v161, 1.0, v161
	v_rcp_f32_e32 v160, v160
	s_ashr_i32 s50, s5, 6
	v_add_f32_e32 v158, 1.0, v158
	v_add_f32_e32 v162, 1.0, v162
	v_rcp_f32_e32 v155, v155
	v_rcp_f32_e32 v156, v156
	v_rcp_f32_e32 v157, v157
	v_rcp_f32_e32 v161, v161
	s_mulk_i32 s12, 0x58
	s_ashr_i32 s51, s50, 31
	v_rcp_f32_e32 v158, v158
	v_rcp_f32_e32 v162, v162
	v_mul_f32_e32 v112, v112, v120
	s_ashr_i32 s5, s12, 31
	v_mul_f32_e32 v120, v112, v159
	v_mul_f32_e32 v112, v113, v121
	s_add_u32 s12, s12, s50
	v_mul_f32_e32 v116, v116, v124
	v_mul_f32_e32 v117, v117, v125
	v_mul_f32_e32 v118, v118, v126
	v_mul_f32_e32 v121, v112, v160
	v_mul_f32_e32 v112, v114, v122
	s_addc_u32 s13, s5, s51
	v_mul_f32_e32 v116, v116, v155
	v_mul_f32_e32 v117, v117, v156
	v_mul_f32_e32 v118, v118, v157
	v_mul_f32_e32 v119, v119, v127
	v_mul_f32_e32 v122, v112, v161
	v_mul_f32_e32 v112, v115, v123
	s_lshl_b64 s[12:13], s[12:13], 15
	v_mul_f32_e32 v119, v119, v158
	v_mul_f32_e32 v115, v112, v162
	v_cvt_pk_bf16_f32 v112, v116, v117
	v_cvt_pk_bf16_f32 v113, v118, v119
	v_lshl_add_u64 v[116:117], v[138:139], 0, s[12:13]
	v_exp_f32_e64 v118, -v104
	v_lshl_add_u64 v[116:117], v[116:117], 0, v[136:137]
	v_exp_f32_e64 v119, -v105
	v_cvt_pk_bf16_f32 v114, v120, v121
	v_cvt_pk_bf16_f32 v115, v122, v115
	global_store_dwordx4 v[116:117], v[112:115], off nt
	v_exp_f32_e64 v120, -v106
	v_exp_f32_e64 v121, -v107
	v_exp_f32_e64 v112, -v108
	v_exp_f32_e64 v113, -v109
	v_exp_f32_e64 v114, -v110
	v_exp_f32_e64 v115, -v111
	v_add_f32_e32 v118, 1.0, v118
	v_add_f32_e32 v119, 1.0, v119
	v_rcp_f32_e32 v118, v118
	v_add_f32_e32 v112, 1.0, v112
	v_add_f32_e32 v120, 1.0, v120
	v_rcp_f32_e32 v119, v119
	v_add_f32_e32 v113, 1.0, v113
	v_add_f32_e32 v121, 1.0, v121
	v_rcp_f32_e32 v112, v112
	v_rcp_f32_e32 v120, v120
	v_add_f32_e32 v114, 1.0, v114
	v_add_f32_e32 v115, 1.0, v115
	v_rcp_f32_e32 v113, v113
	v_rcp_f32_e32 v121, v121
	v_mul_f32_e32 v96, v96, v104
	v_rcp_f32_e32 v114, v114
	v_rcp_f32_e32 v115, v115
	v_mul_f32_e32 v104, v96, v118
	v_mul_f32_e32 v96, v97, v105
	v_mul_f32_e32 v100, v100, v108
	v_mul_f32_e32 v105, v96, v119
	v_mul_f32_e32 v96, v98, v106
	v_mul_f32_e32 v100, v100, v112
	v_mul_f32_e32 v101, v101, v109
	v_mul_f32_e32 v106, v96, v120
	v_mul_f32_e32 v96, v99, v107
	v_mul_f32_e32 v101, v101, v113
	v_mul_f32_e32 v102, v102, v110
	v_mul_f32_e32 v103, v103, v111
	v_mul_f32_e32 v99, v96, v121
	v_cvt_pk_bf16_f32 v96, v100, v101
	v_exp_f32_e64 v100, -v88
	v_mul_f32_e32 v102, v102, v114
	v_mul_f32_e32 v103, v103, v115
	v_cvt_pk_bf16_f32 v97, v102, v103
	v_cvt_pk_bf16_f32 v98, v104, v105
	v_exp_f32_e64 v101, -v89
	v_cvt_pk_bf16_f32 v99, v106, v99
	global_store_dwordx4 v[116:117], v[96:99], off offset:2048 nt
	v_exp_f32_e64 v102, -v90
	v_exp_f32_e64 v103, -v91
	v_exp_f32_e64 v96, -v92
	v_exp_f32_e64 v98, -v94
	v_exp_f32_e64 v97, -v93
	v_exp_f32_e64 v99, -v95
	v_add_f32_e32 v100, 1.0, v100
	v_add_f32_e32 v101, 1.0, v101
	v_rcp_f32_e32 v100, v100
	v_add_f32_e32 v96, 1.0, v96
	v_add_f32_e32 v98, 1.0, v98
	v_add_f32_e32 v102, 1.0, v102
	v_rcp_f32_e32 v101, v101
	v_add_f32_e32 v97, 1.0, v97
	v_add_f32_e32 v99, 1.0, v99
	v_add_f32_e32 v103, 1.0, v103
	v_rcp_f32_e32 v96, v96
	v_rcp_f32_e32 v98, v98
	v_rcp_f32_e32 v102, v102
	v_rcp_f32_e32 v97, v97
	v_rcp_f32_e32 v99, v99
	v_rcp_f32_e32 v103, v103
	v_mul_f32_e32 v80, v80, v88
	v_mul_f32_e32 v88, v80, v100
	v_mul_f32_e32 v80, v81, v89
	v_mul_f32_e32 v84, v84, v92
	v_mul_f32_e32 v86, v86, v94
	v_mul_f32_e32 v89, v80, v101
	v_mul_f32_e32 v80, v82, v90
	v_mul_f32_e32 v84, v84, v96
	v_mul_f32_e32 v85, v85, v93
	v_mul_f32_e32 v86, v86, v98
	v_mul_f32_e32 v87, v87, v95
	v_mul_f32_e32 v90, v80, v102
	v_mul_f32_e32 v80, v83, v91
	v_mul_f32_e32 v85, v85, v97
	v_mul_f32_e32 v87, v87, v99
	v_mul_f32_e32 v83, v80, v103
	v_cvt_pk_bf16_f32 v80, v84, v85
	v_cvt_pk_bf16_f32 v81, v86, v87
	v_add_co_u32_e32 v84, vcc, s62, v116
	v_exp_f32_e64 v86, -v72
	s_nop 0
	v_addc_co_u32_e32 v85, vcc, 0, v117, vcc
	v_exp_f32_e64 v87, -v73
	v_cvt_pk_bf16_f32 v82, v88, v89
	v_cvt_pk_bf16_f32 v83, v90, v83
	global_store_dwordx4 v[84:85], v[80:83], off nt
	v_exp_f32_e64 v88, -v74
	v_exp_f32_e64 v89, -v75
	v_exp_f32_e64 v81, -v77
	v_exp_f32_e64 v80, -v76
	v_exp_f32_e64 v82, -v78
	v_exp_f32_e64 v83, -v79
	v_add_f32_e32 v86, 1.0, v86
	v_add_f32_e32 v87, 1.0, v87
	v_rcp_f32_e32 v86, v86
	v_add_f32_e32 v81, 1.0, v81
	v_add_f32_e32 v88, 1.0, v88
	v_rcp_f32_e32 v87, v87
	v_add_f32_e32 v80, 1.0, v80
	v_add_f32_e32 v82, 1.0, v82
	v_add_f32_e32 v89, 1.0, v89
	v_rcp_f32_e32 v81, v81
	v_rcp_f32_e32 v88, v88
	v_add_f32_e32 v83, 1.0, v83
	v_rcp_f32_e32 v80, v80
	v_rcp_f32_e32 v82, v82
	v_rcp_f32_e32 v89, v89
	v_mul_f32_e32 v64, v64, v72
	v_rcp_f32_e32 v83, v83
	v_mul_f32_e32 v72, v64, v86
	v_mul_f32_e32 v64, v65, v73
	v_mul_f32_e32 v69, v69, v77
	v_mul_f32_e32 v73, v64, v87
	v_mul_f32_e32 v64, v66, v74
	v_mul_f32_e32 v68, v68, v76
	v_mul_f32_e32 v69, v69, v81
	v_mul_f32_e32 v70, v70, v78
	v_mul_f32_e32 v74, v64, v88
	v_mul_f32_e32 v64, v67, v75
	v_mul_f32_e32 v68, v68, v80
	v_mul_f32_e32 v70, v70, v82
	v_mul_f32_e32 v71, v71, v79
	v_mul_f32_e32 v67, v64, v89
	v_cvt_pk_bf16_f32 v64, v68, v69
; __device__ __forceinline__ unsigned cvt_pk_bf16(float lo, float hi) { unsigned r; asm volatile("v_cvt_pk_bf16_f32 %0, %1, %2" : "=v"(r) : "v"(lo), "v"(hi)); return r; }
; #define PG8_BAR __builtin_amdgcn_s_barrier()
;     __device__ __forceinline__ void half(const f32x4 (&acc)[2][4][2], int pm, int ai, int pn, int wr, int wc, int fr, int fq) const {
;     ...
;             for (int m = 0; m < 4; ++m) {
;                 float a[8], e[8];
; #pragma unroll
;                 for (int q = 0; q < 8; ++q) a[q] = acc[0][m][q >> 2][q & 3];
; #pragma unroll
;                 for (int q = 0; q < 8; ++q) e[q] = __builtin_amdgcn_exp2f(-a[q]);
; #pragma unroll
;                 for (int q = 0; q < 8; ++q) e[q] += 1.f;
; #pragma unroll
;                 for (int q = 0; q < 8; ++q) e[q] = __builtin_amdgcn_rcpf(e[q]);
; #pragma unroll
;                 for (int q = 0; q < 8; ++q) a[q] = a[q] * acc[1][m][q >> 2][q & 3] * e[q];
;                 u32x4 w; w.x = cvt_pk_bf16(a[0], a[1]); w.y = cvt_pk_bf16(a[2], a[3]); w.z = cvt_pk_bf16(a[4], a[5]); w.w = cvt_pk_bf16(a[6], a[7]);
;                 const int row = row0 + ai * HALF + m * 16;
;                 bf16_t* dst = O + (((size_t)(row >> 8) * (ldc >> 6) + (col0 >> 6)) * 256 + (row & 255)) * 64 + (col0 & 63);
;                 if (wt) asm volatile("global_store_dwordx4 %0, %1, off sc1\n\ts_nop 1" :: "v"(dst), "v"(w) : "memory"); else *(u32x4*)dst = w; }
; template <class Epi, class Sched, bool ALIGN_EPI = false, bool SP2 = false>
; __device__ __forceinline__ void gemm_phase(PG8_LAS unsigned char* lds, const Gemm g, const Sched& S, const Epi& E) {
;     ...
;         if (!has_next) break;
; #pragma unroll
;         for (int a = 0; a < 2; ++a)
; #pragma unroll
;             for (int b = 0; b < 2; ++b)
; #pragma unroll
;                 for (int m = 0; m < 4; ++m)
; #pragma unroll
;                     for (int n = 0; n < 2; ++n) acc[a][b][m][n] = (f32x4){0.f, 0.f, 0.f, 0.f};
;         cur = nxt; cA = nA; cB = nB; ++ui;
;         if constexpr (ALIGN_EPI) { if (wr == 1) PG8_BAR; }
	v_exp_f32_e64 v69, -v56
	v_mul_f32_e32 v71, v71, v83
	v_cvt_pk_bf16_f32 v65, v70, v71
	v_exp_f32_e64 v70, -v57
	v_cvt_pk_bf16_f32 v66, v72, v73
	v_cvt_pk_bf16_f32 v67, v74, v67
	global_store_dwordx4 v[84:85], v[64:67], off offset:2048 nt
	v_exp_f32_e64 v71, -v58
	v_exp_f32_e64 v72, -v59
	v_exp_f32_e64 v65, -v60
	v_exp_f32_e64 v66, -v61
	v_add_f32_e32 v69, 1.0, v69
	v_add_f32_e32 v70, 1.0, v70
	v_rcp_f32_e32 v69, v69
	v_exp_f32_e64 v67, -v62
	v_add_f32_e32 v65, 1.0, v65
	v_add_f32_e32 v71, 1.0, v71
	v_rcp_f32_e32 v70, v70
	v_exp_f32_e64 v68, -v63
	v_add_f32_e32 v66, 1.0, v66
	v_add_f32_e32 v72, 1.0, v72
	v_rcp_f32_e32 v65, v65
	v_rcp_f32_e32 v71, v71
	v_rcp_f32_e32 v66, v66
	v_rcp_f32_e32 v72, v72
	v_mul_f32_e32 v48, v48, v56
	v_mul_f32_e32 v56, v48, v69
	v_mul_f32_e32 v48, v49, v57
	v_add_u32_e32 v64, s4, v151
	v_add_f32_e32 v67, 1.0, v67
	v_mul_f32_e32 v52, v52, v60
	v_mul_f32_e32 v57, v48, v70
	v_mul_f32_e32 v48, v50, v58
	v_lshrrev_b32_e32 v64, 8, v64
	v_add_f32_e32 v68, 1.0, v68
	v_rcp_f32_e32 v67, v67
	v_mul_f32_e32 v52, v52, v65
	v_mul_f32_e32 v53, v53, v61
	v_mul_f32_e32 v58, v48, v71
	v_mul_f32_e32 v48, v51, v59
	v_rcp_f32_e32 v68, v68
	v_mul_f32_e32 v53, v53, v66
	v_mul_f32_e32 v51, v48, v72
	v_cvt_pk_bf16_f32 v48, v52, v53
	v_mul_i32_i24_e32 v52, 0x58, v64
	v_ashrrev_i32_e32 v53, 31, v52
	v_mul_f32_e32 v54, v54, v62
	v_lshl_add_u64 v[52:53], v[52:53], 0, s[50:51]
	v_mul_f32_e32 v54, v54, v67
	v_mul_f32_e32 v55, v55, v63
	v_lshlrev_b64 v[52:53], 15, v[52:53]
	v_mul_f32_e32 v55, v55, v68
	v_cvt_pk_bf16_f32 v49, v54, v55
	v_lshl_add_u64 v[52:53], v[140:141], 0, v[52:53]
	v_exp_f32_e64 v54, -v40
	v_lshl_add_u64 v[52:53], v[52:53], 0, v[136:137]
	v_exp_f32_e64 v55, -v41
	v_cvt_pk_bf16_f32 v50, v56, v57
	v_cvt_pk_bf16_f32 v51, v58, v51
	global_store_dwordx4 v[52:53], v[48:51], off nt
	v_exp_f32_e64 v56, -v42
	v_exp_f32_e64 v57, -v43
	v_exp_f32_e64 v48, -v44
	v_exp_f32_e64 v49, -v45
	v_exp_f32_e64 v50, -v46
	v_exp_f32_e64 v51, -v47
	v_add_f32_e32 v54, 1.0, v54
	v_add_f32_e32 v55, 1.0, v55
	v_rcp_f32_e32 v54, v54
	v_add_f32_e32 v48, 1.0, v48
	v_add_f32_e32 v56, 1.0, v56
	v_rcp_f32_e32 v55, v55
	v_add_f32_e32 v49, 1.0, v49
	v_add_f32_e32 v57, 1.0, v57
	v_rcp_f32_e32 v48, v48
	v_rcp_f32_e32 v56, v56
	v_add_f32_e32 v50, 1.0, v50
	v_add_f32_e32 v51, 1.0, v51
	v_rcp_f32_e32 v49, v49
	v_rcp_f32_e32 v57, v57
	v_mul_f32_e32 v32, v32, v40
	v_rcp_f32_e32 v50, v50
	v_rcp_f32_e32 v51, v51
	v_mul_f32_e32 v40, v32, v54
	v_mul_f32_e32 v32, v33, v41
	v_mul_f32_e32 v36, v36, v44
	v_mul_f32_e32 v41, v32, v55
	v_mul_f32_e32 v32, v34, v42
	v_mul_f32_e32 v36, v36, v48
	v_mul_f32_e32 v37, v37, v45
	v_mul_f32_e32 v42, v32, v56
	v_mul_f32_e32 v32, v35, v43
	v_mul_f32_e32 v37, v37, v49
	v_mul_f32_e32 v38, v38, v46
	v_mul_f32_e32 v39, v39, v47
	v_mul_f32_e32 v35, v32, v57
	v_cvt_pk_bf16_f32 v32, v36, v37
	v_exp_f32_e64 v36, -v24
	v_mul_f32_e32 v38, v38, v50
	v_mul_f32_e32 v39, v39, v51
	v_cvt_pk_bf16_f32 v33, v38, v39
	v_cvt_pk_bf16_f32 v34, v40, v41
	v_exp_f32_e64 v37, -v25
	v_cvt_pk_bf16_f32 v35, v42, v35
	global_store_dwordx4 v[52:53], v[32:35], off offset:2048 nt
	v_exp_f32_e64 v38, -v26
	v_exp_f32_e64 v39, -v27
	v_exp_f32_e64 v34, -v30
	v_exp_f32_e64 v32, -v28
	v_exp_f32_e64 v33, -v29
	v_exp_f32_e64 v35, -v31
	v_add_f32_e32 v36, 1.0, v36
	v_add_f32_e32 v37, 1.0, v37
	v_rcp_f32_e32 v36, v36
	v_add_f32_e32 v34, 1.0, v34
	v_add_f32_e32 v38, 1.0, v38
	v_rcp_f32_e32 v37, v37
	v_add_f32_e32 v32, 1.0, v32
	v_add_f32_e32 v33, 1.0, v33
	v_add_f32_e32 v35, 1.0, v35
	v_add_f32_e32 v39, 1.0, v39
	v_rcp_f32_e32 v34, v34
	v_rcp_f32_e32 v38, v38
	v_rcp_f32_e32 v32, v32
	v_rcp_f32_e32 v33, v33
	v_rcp_f32_e32 v35, v35
	v_rcp_f32_e32 v39, v39
	v_mul_f32_e32 v16, v16, v24
	v_mul_f32_e32 v24, v16, v36
	v_mul_f32_e32 v16, v17, v25
	v_mul_f32_e32 v22, v22, v30
	v_mul_f32_e32 v25, v16, v37
	v_mul_f32_e32 v16, v18, v26
	v_mul_f32_e32 v20, v20, v28
	v_mul_f32_e32 v21, v21, v29
	v_mul_f32_e32 v22, v22, v34
	v_mul_f32_e32 v23, v23, v31
	v_mul_f32_e32 v26, v16, v38
	v_mul_f32_e32 v16, v19, v27
	v_mul_f32_e32 v20, v20, v32
	v_mul_f32_e32 v21, v21, v33
	v_mul_f32_e32 v23, v23, v35
	v_mul_f32_e32 v19, v16, v39
	v_cvt_pk_bf16_f32 v16, v20, v21
	v_cvt_pk_bf16_f32 v17, v22, v23
	v_exp_f32_e64 v22, -v8
	v_exp_f32_e64 v23, -v9
	v_cvt_pk_bf16_f32 v18, v24, v25
	v_add_co_u32_e32 v20, vcc, s62, v52
	v_exp_f32_e64 v24, -v10
	v_cvt_pk_bf16_f32 v19, v26, v19
	s_nop 0
	v_addc_co_u32_e32 v21, vcc, 0, v53, vcc
	v_exp_f32_e64 v25, -v11
	global_store_dwordx4 v[20:21], v[16:19], off nt
	v_add_f32_e32 v22, 1.0, v22
	v_add_f32_e32 v23, 1.0, v23
	v_exp_f32_e64 v16, -v12
	v_exp_f32_e64 v17, -v13
	v_exp_f32_e64 v18, -v14
	v_exp_f32_e64 v19, -v15
	v_rcp_f32_e32 v22, v22
	v_add_f32_e32 v24, 1.0, v24
	v_rcp_f32_e32 v23, v23
	v_add_f32_e32 v25, 1.0, v25
	v_rcp_f32_e32 v24, v24
	v_add_f32_e32 v16, 1.0, v16
	v_add_f32_e32 v17, 1.0, v17
	v_add_f32_e32 v18, 1.0, v18
	v_add_f32_e32 v19, 1.0, v19
	v_rcp_f32_e32 v25, v25
	v_mul_f32_e32 v0, v0, v8
	v_rcp_f32_e32 v16, v16
	v_rcp_f32_e32 v17, v17
	v_rcp_f32_e32 v18, v18
	v_rcp_f32_e32 v19, v19
	v_mul_f32_e32 v8, v0, v22
	v_mul_f32_e32 v0, v1, v9
	v_mul_f32_e32 v9, v0, v23
	v_mul_f32_e32 v0, v2, v10
	v_mul_f32_e32 v10, v0, v24
	v_mul_f32_e32 v0, v3, v11
	v_mul_f32_e32 v4, v4, v12
	v_mul_f32_e32 v5, v5, v13
	v_mul_f32_e32 v6, v6, v14
	v_mul_f32_e32 v7, v7, v15
	v_mul_f32_e32 v3, v0, v25
	s_andn2_b64 vcc, exec, s[42:43]
	s_mov_b64 s[4:5], -1
	v_mul_f32_e32 v4, v4, v16
	v_mul_f32_e32 v5, v5, v17
	v_mul_f32_e32 v6, v6, v18
	v_mul_f32_e32 v7, v7, v19
	v_cvt_pk_bf16_f32 v0, v4, v5
	v_cvt_pk_bf16_f32 v1, v6, v7
	v_cvt_pk_bf16_f32 v2, v8, v9
	v_cvt_pk_bf16_f32 v3, v10, v3
	global_store_dwordx4 v[20:21], v[0:3], off offset:2048 nt
	s_cbranch_vccnz .LBB0_1299
	s_andn2_b64 vcc, exec, s[0:1]
	s_cbranch_vccnz .LBB0_1298
	s_barrier
	s_branch .LBB0_1298

; __device__ __forceinline__ unsigned cvt_pk_bf16(float lo, float hi) { unsigned r; asm volatile("v_cvt_pk_bf16_f32 %0, %1, %2" : "=v"(r) : "v"(lo), "v"(hi)); return r; }
;     __device__ __forceinline__ void half(const f32x4 (&acc)[2][4][2], int pm, int ai, int pn, int wr, int wc, int fr, int fq) const {
;     ...
;             for (int m = 0; m < 4; ++m) {
;                 float a[8], e[8];
; #pragma unroll
;                 for (int q = 0; q < 8; ++q) a[q] = acc[0][m][q >> 2][q & 3];
; #pragma unroll
;                 for (int q = 0; q < 8; ++q) e[q] = __builtin_amdgcn_exp2f(-a[q]);
; #pragma unroll
;                 for (int q = 0; q < 8; ++q) e[q] += 1.f;
; #pragma unroll
;                 for (int q = 0; q < 8; ++q) e[q] = __builtin_amdgcn_rcpf(e[q]);
; #pragma unroll
;                 for (int q = 0; q < 8; ++q) a[q] = a[q] * acc[1][m][q >> 2][q & 3] * e[q];
;                 u32x4 w; w.x = cvt_pk_bf16(a[0], a[1]); w.y = cvt_pk_bf16(a[2], a[3]); w.z = cvt_pk_bf16(a[4], a[5]); w.w = cvt_pk_bf16(a[6], a[7]);
;                 const int row = row0 + ai * HALF + m * 16;
;                 bf16_t* dst = O + (((size_t)(row >> 8) * (ldc >> 6) + (col0 >> 6)) * 256 + (row & 255)) * 64 + (col0 & 63);
;                 if (wt) asm volatile("global_store_dwordx4 %0, %1, off sc1\n\ts_nop 1" :: "v"(dst), "v"(w) : "memory"); else *(u32x4*)dst = w; }
.LBB0_1660:
	v_exp_f32_e64 v159, -v120
	v_exp_f32_e64 v160, -v121
	v_exp_f32_e64 v155, -v124
	v_exp_f32_e64 v156, -v125
	v_exp_f32_e64 v157, -v126
	v_exp_f32_e64 v161, -v122
	v_exp_f32_e64 v158, -v127
	v_exp_f32_e64 v162, -v123
	s_lshl_b32 s4, s62, 8
	v_add_f32_e32 v159, 1.0, v159
	s_lshl_b32 s5, s60, 7
	s_add_i32 s12, s4, s42
	v_add_f32_e32 v160, 1.0, v160
	v_rcp_f32_e32 v159, v159
	s_or_b32 s5, s5, s43
	s_ashr_i32 s12, s12, 8
	v_add_f32_e32 v155, 1.0, v155
	v_add_f32_e32 v156, 1.0, v156
	v_add_f32_e32 v157, 1.0, v157
	v_add_f32_e32 v161, 1.0, v161
	v_rcp_f32_e32 v160, v160
	s_ashr_i32 s50, s5, 6
	v_add_f32_e32 v158, 1.0, v158
	v_add_f32_e32 v162, 1.0, v162
	v_rcp_f32_e32 v155, v155
	v_rcp_f32_e32 v156, v156
	v_rcp_f32_e32 v157, v157
	v_rcp_f32_e32 v161, v161
	s_mulk_i32 s12, 0x58
	s_ashr_i32 s51, s50, 31
	v_rcp_f32_e32 v158, v158
	v_rcp_f32_e32 v162, v162
	v_mul_f32_e32 v112, v112, v120
	s_ashr_i32 s5, s12, 31
	v_mul_f32_e32 v120, v112, v159
	v_mul_f32_e32 v112, v113, v121
	s_add_u32 s12, s12, s50
	v_mul_f32_e32 v116, v116, v124
	v_mul_f32_e32 v117, v117, v125
	v_mul_f32_e32 v118, v118, v126
	v_mul_f32_e32 v121, v112, v160
	v_mul_f32_e32 v112, v114, v122
	s_addc_u32 s13, s5, s51
	v_mul_f32_e32 v116, v116, v155
	v_mul_f32_e32 v117, v117, v156
	v_mul_f32_e32 v118, v118, v157
	v_mul_f32_e32 v119, v119, v127
	v_mul_f32_e32 v122, v112, v161
	v_mul_f32_e32 v112, v115, v123
	s_lshl_b64 s[12:13], s[12:13], 15
	v_mul_f32_e32 v119, v119, v158
	v_mul_f32_e32 v115, v112, v162
	v_cvt_pk_bf16_f32 v112, v116, v117
	v_cvt_pk_bf16_f32 v113, v118, v119
	v_lshl_add_u64 v[116:117], v[138:139], 0, s[12:13]
	v_exp_f32_e64 v118, -v104
	v_lshl_add_u64 v[116:117], v[116:117], 0, v[136:137]
	v_exp_f32_e64 v119, -v105
	v_cvt_pk_bf16_f32 v114, v120, v121
	v_cvt_pk_bf16_f32 v115, v122, v115
	global_store_dwordx4 v[116:117], v[112:115], off nt
	v_exp_f32_e64 v120, -v106
	v_exp_f32_e64 v121, -v107
	v_exp_f32_e64 v112, -v108
	v_exp_f32_e64 v113, -v109
	v_exp_f32_e64 v114, -v110
	v_exp_f32_e64 v115, -v111
	v_add_f32_e32 v118, 1.0, v118
	v_add_f32_e32 v119, 1.0, v119
	v_rcp_f32_e32 v118, v118
	v_add_f32_e32 v112, 1.0, v112
	v_add_f32_e32 v120, 1.0, v120
	v_rcp_f32_e32 v119, v119
	v_add_f32_e32 v113, 1.0, v113
	v_add_f32_e32 v121, 1.0, v121
	v_rcp_f32_e32 v112, v112
	v_rcp_f32_e32 v120, v120
	v_add_f32_e32 v114, 1.0, v114
	v_add_f32_e32 v115, 1.0, v115
	v_rcp_f32_e32 v113, v113
	v_rcp_f32_e32 v121, v121
	v_mul_f32_e32 v96, v96, v104
	v_rcp_f32_e32 v114, v114
	v_rcp_f32_e32 v115, v115
	v_mul_f32_e32 v104, v96, v118
	v_mul_f32_e32 v96, v97, v105
	v_mul_f32_e32 v100, v100, v108
	v_mul_f32_e32 v105, v96, v119
	v_mul_f32_e32 v96, v98, v106
	v_mul_f32_e32 v100, v100, v112
	v_mul_f32_e32 v101, v101, v109
	v_mul_f32_e32 v106, v96, v120
	v_mul_f32_e32 v96, v99, v107
	v_mul_f32_e32 v101, v101, v113
	v_mul_f32_e32 v102, v102, v110
	v_mul_f32_e32 v103, v103, v111
	v_mul_f32_e32 v99, v96, v121
	v_cvt_pk_bf16_f32 v96, v100, v101
	v_exp_f32_e64 v100, -v88
	v_mul_f32_e32 v102, v102, v114
	v_mul_f32_e32 v103, v103, v115
	v_cvt_pk_bf16_f32 v97, v102, v103
	v_cvt_pk_bf16_f32 v98, v104, v105
	v_exp_f32_e64 v101, -v89
	v_cvt_pk_bf16_f32 v99, v106, v99
	global_store_dwordx4 v[116:117], v[96:99], off offset:2048 nt
	v_exp_f32_e64 v102, -v90
	v_exp_f32_e64 v103, -v91
	v_exp_f32_e64 v96, -v92
	v_exp_f32_e64 v98, -v94
	v_exp_f32_e64 v97, -v93
	v_exp_f32_e64 v99, -v95
	v_add_f32_e32 v100, 1.0, v100
	v_add_f32_e32 v101, 1.0, v101
	v_rcp_f32_e32 v100, v100
	v_add_f32_e32 v96, 1.0, v96
	v_add_f32_e32 v98, 1.0, v98
	v_add_f32_e32 v102, 1.0, v102
	v_rcp_f32_e32 v101, v101
	v_add_f32_e32 v97, 1.0, v97
	v_add_f32_e32 v99, 1.0, v99
	v_add_f32_e32 v103, 1.0, v103
	v_rcp_f32_e32 v96, v96
	v_rcp_f32_e32 v98, v98
	v_rcp_f32_e32 v102, v102
	v_rcp_f32_e32 v97, v97
	v_rcp_f32_e32 v99, v99
	v_rcp_f32_e32 v103, v103
	v_mul_f32_e32 v80, v80, v88
	v_mul_f32_e32 v88, v80, v100
	v_mul_f32_e32 v80, v81, v89
	v_mul_f32_e32 v84, v84, v92
	v_mul_f32_e32 v86, v86, v94
	v_mul_f32_e32 v89, v80, v101
	v_mul_f32_e32 v80, v82, v90
	v_mul_f32_e32 v84, v84, v96
	v_mul_f32_e32 v85, v85, v93
	v_mul_f32_e32 v86, v86, v98
	v_mul_f32_e32 v87, v87, v95
	v_mul_f32_e32 v90, v80, v102
	v_mul_f32_e32 v80, v83, v91
	v_mul_f32_e32 v85, v85, v97
	v_mul_f32_e32 v87, v87, v99
	v_mul_f32_e32 v83, v80, v103
	v_cvt_pk_bf16_f32 v80, v84, v85
	v_cvt_pk_bf16_f32 v81, v86, v87
	v_add_co_u32_e32 v84, vcc, s61, v116
	v_exp_f32_e64 v86, -v72
	s_nop 0
	v_addc_co_u32_e32 v85, vcc, 0, v117, vcc
	v_exp_f32_e64 v87, -v73
	v_cvt_pk_bf16_f32 v82, v88, v89
	v_cvt_pk_bf16_f32 v83, v90, v83
	global_store_dwordx4 v[84:85], v[80:83], off nt
	v_exp_f32_e64 v88, -v74
	v_exp_f32_e64 v89, -v75
	v_exp_f32_e64 v81, -v77
	v_exp_f32_e64 v80, -v76
	v_exp_f32_e64 v82, -v78
	v_exp_f32_e64 v83, -v79
	v_add_f32_e32 v86, 1.0, v86
	v_add_f32_e32 v87, 1.0, v87
	v_rcp_f32_e32 v86, v86
	v_add_f32_e32 v81, 1.0, v81
	v_add_f32_e32 v88, 1.0, v88
	v_rcp_f32_e32 v87, v87
	v_add_f32_e32 v80, 1.0, v80
	v_add_f32_e32 v82, 1.0, v82
	v_add_f32_e32 v89, 1.0, v89
	v_rcp_f32_e32 v81, v81
	v_rcp_f32_e32 v88, v88
	v_add_f32_e32 v83, 1.0, v83
	v_rcp_f32_e32 v80, v80
	v_rcp_f32_e32 v82, v82
	v_rcp_f32_e32 v89, v89
	v_mul_f32_e32 v64, v64, v72
	v_rcp_f32_e32 v83, v83
	v_mul_f32_e32 v72, v64, v86
	v_mul_f32_e32 v64, v65, v73
	v_mul_f32_e32 v69, v69, v77
	v_mul_f32_e32 v73, v64, v87
	v_mul_f32_e32 v64, v66, v74
	v_mul_f32_e32 v68, v68, v76
	v_mul_f32_e32 v69, v69, v81
	v_mul_f32_e32 v70, v70, v78
	v_mul_f32_e32 v74, v64, v88
	v_mul_f32_e32 v64, v67, v75
	v_mul_f32_e32 v68, v68, v80
	v_mul_f32_e32 v70, v70, v82
	v_mul_f32_e32 v71, v71, v79
	v_mul_f32_e32 v67, v64, v89
	v_cvt_pk_bf16_f32 v64, v68, v69
; __device__ __forceinline__ unsigned cvt_pk_bf16(float lo, float hi) { unsigned r; asm volatile("v_cvt_pk_bf16_f32 %0, %1, %2" : "=v"(r) : "v"(lo), "v"(hi)); return r; }
; #define PG8_BAR __builtin_amdgcn_s_barrier()
;     __device__ __forceinline__ void half(const f32x4 (&acc)[2][4][2], int pm, int ai, int pn, int wr, int wc, int fr, int fq) const {
;     ...
;             for (int m = 0; m < 4; ++m) {
;                 float a[8], e[8];
; #pragma unroll
;                 for (int q = 0; q < 8; ++q) a[q] = acc[0][m][q >> 2][q & 3];
; #pragma unroll
;                 for (int q = 0; q < 8; ++q) e[q] = __builtin_amdgcn_exp2f(-a[q]);
; #pragma unroll
;                 for (int q = 0; q < 8; ++q) e[q] += 1.f;
; #pragma unroll
;                 for (int q = 0; q < 8; ++q) e[q] = __builtin_amdgcn_rcpf(e[q]);
; #pragma unroll
;                 for (int q = 0; q < 8; ++q) a[q] = a[q] * acc[1][m][q >> 2][q & 3] * e[q];
;                 u32x4 w; w.x = cvt_pk_bf16(a[0], a[1]); w.y = cvt_pk_bf16(a[2], a[3]); w.z = cvt_pk_bf16(a[4], a[5]); w.w = cvt_pk_bf16(a[6], a[7]);
;                 const int row = row0 + ai * HALF + m * 16;
;                 bf16_t* dst = O + (((size_t)(row >> 8) * (ldc >> 6) + (col0 >> 6)) * 256 + (row & 255)) * 64 + (col0 & 63);
;                 if (wt) asm volatile("global_store_dwordx4 %0, %1, off sc1\n\ts_nop 1" :: "v"(dst), "v"(w) : "memory"); else *(u32x4*)dst = w; }
; template <class Epi, class Sched, bool ALIGN_EPI = false, bool SP2 = false>
; __device__ __forceinline__ void gemm_phase(PG8_LAS unsigned char* lds, const Gemm g, const Sched& S, const Epi& E) {
;     ...
;         if (!has_next) break;
; #pragma unroll
;         for (int a = 0; a < 2; ++a)
; #pragma unroll
;             for (int b = 0; b < 2; ++b)
; #pragma unroll
;                 for (int m = 0; m < 4; ++m)
; #pragma unroll
;                     for (int n = 0; n < 2; ++n) acc[a][b][m][n] = (f32x4){0.f, 0.f, 0.f, 0.f};
;         cur = nxt; cA = nA; cB = nB; ++ui;
;         if constexpr (ALIGN_EPI) { if (wr == 1) PG8_BAR; }
	v_exp_f32_e64 v69, -v56
	v_mul_f32_e32 v71, v71, v83
	v_cvt_pk_bf16_f32 v65, v70, v71
	v_exp_f32_e64 v70, -v57
	v_cvt_pk_bf16_f32 v66, v72, v73
	v_cvt_pk_bf16_f32 v67, v74, v67
	global_store_dwordx4 v[84:85], v[64:67], off offset:2048 nt
	v_exp_f32_e64 v71, -v58
	v_exp_f32_e64 v72, -v59
	v_exp_f32_e64 v65, -v60
	v_exp_f32_e64 v66, -v61
	v_add_f32_e32 v69, 1.0, v69
	v_add_f32_e32 v70, 1.0, v70
	v_rcp_f32_e32 v69, v69
	v_exp_f32_e64 v67, -v62
	v_add_f32_e32 v65, 1.0, v65
	v_add_f32_e32 v71, 1.0, v71
	v_rcp_f32_e32 v70, v70
	v_exp_f32_e64 v68, -v63
	v_add_f32_e32 v66, 1.0, v66
	v_add_f32_e32 v72, 1.0, v72
	v_rcp_f32_e32 v65, v65
	v_rcp_f32_e32 v71, v71
	v_rcp_f32_e32 v66, v66
	v_rcp_f32_e32 v72, v72
	v_mul_f32_e32 v48, v48, v56
	v_mul_f32_e32 v56, v48, v69
	v_mul_f32_e32 v48, v49, v57
	v_add_u32_e32 v64, s4, v151
	v_add_f32_e32 v67, 1.0, v67
	v_mul_f32_e32 v52, v52, v60
	v_mul_f32_e32 v57, v48, v70
	v_mul_f32_e32 v48, v50, v58
	v_lshrrev_b32_e32 v64, 8, v64
	v_add_f32_e32 v68, 1.0, v68
	v_rcp_f32_e32 v67, v67
	v_mul_f32_e32 v52, v52, v65
	v_mul_f32_e32 v53, v53, v61
	v_mul_f32_e32 v58, v48, v71
	v_mul_f32_e32 v48, v51, v59
	v_rcp_f32_e32 v68, v68
	v_mul_f32_e32 v53, v53, v66
	v_mul_f32_e32 v51, v48, v72
	v_cvt_pk_bf16_f32 v48, v52, v53
	v_mul_i32_i24_e32 v52, 0x58, v64
	v_ashrrev_i32_e32 v53, 31, v52
	v_mul_f32_e32 v54, v54, v62
	v_lshl_add_u64 v[52:53], v[52:53], 0, s[50:51]
	v_mul_f32_e32 v54, v54, v67
	v_mul_f32_e32 v55, v55, v63
	v_lshlrev_b64 v[52:53], 15, v[52:53]
	v_mul_f32_e32 v55, v55, v68
	v_cvt_pk_bf16_f32 v49, v54, v55
	v_lshl_add_u64 v[52:53], v[140:141], 0, v[52:53]
	v_exp_f32_e64 v54, -v40
	v_lshl_add_u64 v[52:53], v[52:53], 0, v[136:137]
	v_exp_f32_e64 v55, -v41
	v_cvt_pk_bf16_f32 v50, v56, v57
	v_cvt_pk_bf16_f32 v51, v58, v51
	global_store_dwordx4 v[52:53], v[48:51], off nt
	v_exp_f32_e64 v56, -v42
	v_exp_f32_e64 v57, -v43
	v_exp_f32_e64 v48, -v44
	v_exp_f32_e64 v49, -v45
	v_exp_f32_e64 v50, -v46
	v_exp_f32_e64 v51, -v47
	v_add_f32_e32 v54, 1.0, v54
	v_add_f32_e32 v55, 1.0, v55
	v_rcp_f32_e32 v54, v54
	v_add_f32_e32 v48, 1.0, v48
	v_add_f32_e32 v56, 1.0, v56
	v_rcp_f32_e32 v55, v55
	v_add_f32_e32 v49, 1.0, v49
	v_add_f32_e32 v57, 1.0, v57
	v_rcp_f32_e32 v48, v48
	v_rcp_f32_e32 v56, v56
	v_add_f32_e32 v50, 1.0, v50
	v_add_f32_e32 v51, 1.0, v51
	v_rcp_f32_e32 v49, v49
	v_rcp_f32_e32 v57, v57
	v_mul_f32_e32 v32, v32, v40
	v_rcp_f32_e32 v50, v50
	v_rcp_f32_e32 v51, v51
	v_mul_f32_e32 v40, v32, v54
	v_mul_f32_e32 v32, v33, v41
	v_mul_f32_e32 v36, v36, v44
	v_mul_f32_e32 v41, v32, v55
	v_mul_f32_e32 v32, v34, v42
	v_mul_f32_e32 v36, v36, v48
	v_mul_f32_e32 v37, v37, v45
	v_mul_f32_e32 v42, v32, v56
	v_mul_f32_e32 v32, v35, v43
	v_mul_f32_e32 v37, v37, v49
	v_mul_f32_e32 v38, v38, v46
	v_mul_f32_e32 v39, v39, v47
	v_mul_f32_e32 v35, v32, v57
	v_cvt_pk_bf16_f32 v32, v36, v37
	v_exp_f32_e64 v36, -v24
	v_mul_f32_e32 v38, v38, v50
	v_mul_f32_e32 v39, v39, v51
	v_cvt_pk_bf16_f32 v33, v38, v39
	v_cvt_pk_bf16_f32 v34, v40, v41
	v_exp_f32_e64 v37, -v25
	v_cvt_pk_bf16_f32 v35, v42, v35
	global_store_dwordx4 v[52:53], v[32:35], off offset:2048 nt
	v_exp_f32_e64 v38, -v26
	v_exp_f32_e64 v39, -v27
	v_exp_f32_e64 v34, -v30
	v_exp_f32_e64 v32, -v28
	v_exp_f32_e64 v33, -v29
	v_exp_f32_e64 v35, -v31
	v_add_f32_e32 v36, 1.0, v36
	v_add_f32_e32 v37, 1.0, v37
	v_rcp_f32_e32 v36, v36
	v_add_f32_e32 v34, 1.0, v34
	v_add_f32_e32 v38, 1.0, v38
	v_rcp_f32_e32 v37, v37
	v_add_f32_e32 v32, 1.0, v32
	v_add_f32_e32 v33, 1.0, v33
	v_add_f32_e32 v35, 1.0, v35
	v_add_f32_e32 v39, 1.0, v39
	v_rcp_f32_e32 v34, v34
	v_rcp_f32_e32 v38, v38
	v_rcp_f32_e32 v32, v32
	v_rcp_f32_e32 v33, v33
	v_rcp_f32_e32 v35, v35
	v_rcp_f32_e32 v39, v39
	v_mul_f32_e32 v16, v16, v24
	v_mul_f32_e32 v24, v16, v36
	v_mul_f32_e32 v16, v17, v25
	v_mul_f32_e32 v22, v22, v30
	v_mul_f32_e32 v25, v16, v37
	v_mul_f32_e32 v16, v18, v26
	v_mul_f32_e32 v20, v20, v28
	v_mul_f32_e32 v21, v21, v29
	v_mul_f32_e32 v22, v22, v34
	v_mul_f32_e32 v23, v23, v31
	v_mul_f32_e32 v26, v16, v38
	v_mul_f32_e32 v16, v19, v27
	v_mul_f32_e32 v20, v20, v32
	v_mul_f32_e32 v21, v21, v33
	v_mul_f32_e32 v23, v23, v35
	v_mul_f32_e32 v19, v16, v39
	v_cvt_pk_bf16_f32 v16, v20, v21
	v_cvt_pk_bf16_f32 v17, v22, v23
	v_exp_f32_e64 v22, -v8
	v_exp_f32_e64 v23, -v9
	v_cvt_pk_bf16_f32 v18, v24, v25
	v_add_co_u32_e32 v20, vcc, s61, v52
	v_exp_f32_e64 v24, -v10
	v_cvt_pk_bf16_f32 v19, v26, v19
	s_nop 0
	v_addc_co_u32_e32 v21, vcc, 0, v53, vcc
	v_exp_f32_e64 v25, -v11
	global_store_dwordx4 v[20:21], v[16:19], off nt
	v_add_f32_e32 v22, 1.0, v22
	v_add_f32_e32 v23, 1.0, v23
	v_exp_f32_e64 v16, -v12
	v_exp_f32_e64 v17, -v13
	v_exp_f32_e64 v18, -v14
	v_exp_f32_e64 v19, -v15
	v_rcp_f32_e32 v22, v22
	v_add_f32_e32 v24, 1.0, v24
	v_rcp_f32_e32 v23, v23
	v_add_f32_e32 v25, 1.0, v25
	v_rcp_f32_e32 v24, v24
	v_add_f32_e32 v16, 1.0, v16
	v_add_f32_e32 v17, 1.0, v17
	v_add_f32_e32 v18, 1.0, v18
	v_add_f32_e32 v19, 1.0, v19
	v_rcp_f32_e32 v25, v25
	v_mul_f32_e32 v0, v0, v8
	v_rcp_f32_e32 v16, v16
	v_rcp_f32_e32 v17, v17
	v_rcp_f32_e32 v18, v18
	v_rcp_f32_e32 v19, v19
	v_mul_f32_e32 v8, v0, v22
	v_mul_f32_e32 v0, v1, v9
	v_mul_f32_e32 v9, v0, v23
	v_mul_f32_e32 v0, v2, v10
	v_mul_f32_e32 v10, v0, v24
	v_mul_f32_e32 v0, v3, v11
	v_mul_f32_e32 v4, v4, v12
	v_mul_f32_e32 v5, v5, v13
	v_mul_f32_e32 v6, v6, v14
	v_mul_f32_e32 v7, v7, v15
	v_mul_f32_e32 v3, v0, v25
	s_andn2_b64 vcc, exec, s[44:45]
	s_mov_b64 s[4:5], -1
	v_mul_f32_e32 v4, v4, v16
	v_mul_f32_e32 v5, v5, v17
	v_mul_f32_e32 v6, v6, v18
	v_mul_f32_e32 v7, v7, v19
	v_cvt_pk_bf16_f32 v0, v4, v5
	v_cvt_pk_bf16_f32 v1, v6, v7
	v_cvt_pk_bf16_f32 v2, v8, v9
	v_cvt_pk_bf16_f32 v3, v10, v3
	global_store_dwordx4 v[20:21], v[0:3], off offset:2048 nt
	s_cbranch_vccnz .LBB0_1649
	s_andn2_b64 vcc, exec, s[0:1]
	s_cbranch_vccnz .LBB0_1648
	s_barrier
	s_branch .LBB0_1648

; __device__ __forceinline__ unsigned cvt_pk_bf16(float lo, float hi) { unsigned r; asm volatile("v_cvt_pk_bf16_f32 %0, %1, %2" : "=v"(r) : "v"(lo), "v"(hi)); return r; }
;     __device__ __forceinline__ void half(const f32x4 (&acc)[2][4][2], int pm, int ai, int pn, int wr, int wc, int fr, int fq) const {
;     ...
;             for (int m = 0; m < 4; ++m) {
;                 float a[8], e[8];
; #pragma unroll
;                 for (int q = 0; q < 8; ++q) a[q] = acc[0][m][q >> 2][q & 3];
; #pragma unroll
;                 for (int q = 0; q < 8; ++q) e[q] = __builtin_amdgcn_exp2f(-a[q]);
; #pragma unroll
;                 for (int q = 0; q < 8; ++q) e[q] += 1.f;
; #pragma unroll
;                 for (int q = 0; q < 8; ++q) e[q] = __builtin_amdgcn_rcpf(e[q]);
; #pragma unroll
;                 for (int q = 0; q < 8; ++q) a[q] = a[q] * acc[1][m][q >> 2][q & 3] * e[q];
;                 u32x4 w; w.x = cvt_pk_bf16(a[0], a[1]); w.y = cvt_pk_bf16(a[2], a[3]); w.z = cvt_pk_bf16(a[4], a[5]); w.w = cvt_pk_bf16(a[6], a[7]);
;                 const int row = row0 + ai * HALF + m * 16;
;                 bf16_t* dst = O + (((size_t)(row >> 8) * (ldc >> 6) + (col0 >> 6)) * 256 + (row & 255)) * 64 + (col0 & 63);
;                 if (wt) asm volatile("global_store_dwordx4 %0, %1, off sc1\n\ts_nop 1" :: "v"(dst), "v"(w) : "memory"); else *(u32x4*)dst = w; }
.LBB0_3061:
	v_exp_f32_e64 v159, -v120
	v_exp_f32_e64 v160, -v121
	v_exp_f32_e64 v155, -v124
	v_exp_f32_e64 v156, -v125
	v_exp_f32_e64 v157, -v126
	v_exp_f32_e64 v161, -v122
	v_exp_f32_e64 v158, -v127
	v_exp_f32_e64 v162, -v123
	s_lshl_b32 s4, s38, 8
	v_add_f32_e32 v159, 1.0, v159
	s_lshl_b32 s5, s34, 7
	s_add_i32 s12, s4, s46
	v_add_f32_e32 v160, 1.0, v160
	v_rcp_f32_e32 v159, v159
	s_or_b32 s5, s5, s47
	s_ashr_i32 s12, s12, 8
	v_add_f32_e32 v155, 1.0, v155
	v_add_f32_e32 v156, 1.0, v156
	v_add_f32_e32 v157, 1.0, v157
	v_add_f32_e32 v161, 1.0, v161
	v_rcp_f32_e32 v160, v160
	s_ashr_i32 s34, s5, 6
	v_add_f32_e32 v158, 1.0, v158
	v_add_f32_e32 v162, 1.0, v162
	v_rcp_f32_e32 v155, v155
	v_rcp_f32_e32 v156, v156
	v_rcp_f32_e32 v157, v157
	v_rcp_f32_e32 v161, v161
	s_mulk_i32 s12, 0x58
	s_ashr_i32 s35, s34, 31
	v_rcp_f32_e32 v158, v158
	v_rcp_f32_e32 v162, v162
	v_mul_f32_e32 v112, v112, v120
	s_ashr_i32 s5, s12, 31
	v_mul_f32_e32 v120, v112, v159
	v_mul_f32_e32 v112, v113, v121
	s_add_u32 s12, s12, s34
	v_mul_f32_e32 v116, v116, v124
	v_mul_f32_e32 v117, v117, v125
	v_mul_f32_e32 v118, v118, v126
	v_mul_f32_e32 v121, v112, v160
	v_mul_f32_e32 v112, v114, v122
	s_addc_u32 s13, s5, s35
	v_mul_f32_e32 v116, v116, v155
	v_mul_f32_e32 v117, v117, v156
	v_mul_f32_e32 v118, v118, v157
	v_mul_f32_e32 v119, v119, v127
	v_mul_f32_e32 v122, v112, v161
	v_mul_f32_e32 v112, v115, v123
	s_lshl_b64 s[12:13], s[12:13], 15
	v_mul_f32_e32 v119, v119, v158
	v_mul_f32_e32 v115, v112, v162
	v_cvt_pk_bf16_f32 v112, v116, v117
	v_cvt_pk_bf16_f32 v113, v118, v119
	v_lshl_add_u64 v[116:117], v[138:139], 0, s[12:13]
	v_exp_f32_e64 v118, -v104
	v_lshl_add_u64 v[116:117], v[116:117], 0, v[136:137]
	v_exp_f32_e64 v119, -v105
	v_cvt_pk_bf16_f32 v114, v120, v121
	v_cvt_pk_bf16_f32 v115, v122, v115
	global_store_dwordx4 v[116:117], v[112:115], off nt
	v_exp_f32_e64 v120, -v106
	v_exp_f32_e64 v121, -v107
	v_exp_f32_e64 v112, -v108
	v_exp_f32_e64 v113, -v109
	v_exp_f32_e64 v114, -v110
	v_exp_f32_e64 v115, -v111
	v_add_f32_e32 v118, 1.0, v118
	v_add_f32_e32 v119, 1.0, v119
	v_rcp_f32_e32 v118, v118
	v_add_f32_e32 v112, 1.0, v112
	v_add_f32_e32 v120, 1.0, v120
	v_rcp_f32_e32 v119, v119
	v_add_f32_e32 v113, 1.0, v113
	v_add_f32_e32 v121, 1.0, v121
	v_rcp_f32_e32 v112, v112
	v_rcp_f32_e32 v120, v120
	v_add_f32_e32 v114, 1.0, v114
	v_add_f32_e32 v115, 1.0, v115
	v_rcp_f32_e32 v113, v113
	v_rcp_f32_e32 v121, v121
	v_mul_f32_e32 v96, v96, v104
	v_rcp_f32_e32 v114, v114
	v_rcp_f32_e32 v115, v115
	v_mul_f32_e32 v104, v96, v118
	v_mul_f32_e32 v96, v97, v105
	v_mul_f32_e32 v100, v100, v108
	v_mul_f32_e32 v105, v96, v119
	v_mul_f32_e32 v96, v98, v106
	v_mul_f32_e32 v100, v100, v112
	v_mul_f32_e32 v101, v101, v109
	v_mul_f32_e32 v106, v96, v120
	v_mul_f32_e32 v96, v99, v107
	v_mul_f32_e32 v101, v101, v113
	v_mul_f32_e32 v102, v102, v110
	v_mul_f32_e32 v103, v103, v111
	v_mul_f32_e32 v99, v96, v121
	v_cvt_pk_bf16_f32 v96, v100, v101
	v_exp_f32_e64 v100, -v88
	v_mul_f32_e32 v102, v102, v114
	v_mul_f32_e32 v103, v103, v115
	v_cvt_pk_bf16_f32 v97, v102, v103
	v_cvt_pk_bf16_f32 v98, v104, v105
	v_exp_f32_e64 v101, -v89
	v_cvt_pk_bf16_f32 v99, v106, v99
	global_store_dwordx4 v[116:117], v[96:99], off offset:2048 nt
	v_exp_f32_e64 v102, -v90
	v_exp_f32_e64 v103, -v91
	v_exp_f32_e64 v96, -v92
	v_exp_f32_e64 v98, -v94
	v_exp_f32_e64 v97, -v93
	v_exp_f32_e64 v99, -v95
	v_add_f32_e32 v100, 1.0, v100
	v_add_f32_e32 v101, 1.0, v101
	v_rcp_f32_e32 v100, v100
	v_add_f32_e32 v96, 1.0, v96
	v_add_f32_e32 v98, 1.0, v98
	v_add_f32_e32 v102, 1.0, v102
	v_rcp_f32_e32 v101, v101
	v_add_f32_e32 v97, 1.0, v97
	v_add_f32_e32 v99, 1.0, v99
	v_add_f32_e32 v103, 1.0, v103
	v_rcp_f32_e32 v96, v96
	v_rcp_f32_e32 v98, v98
	v_rcp_f32_e32 v102, v102
	v_rcp_f32_e32 v97, v97
	v_rcp_f32_e32 v99, v99
	v_rcp_f32_e32 v103, v103
	v_mul_f32_e32 v80, v80, v88
	v_mul_f32_e32 v88, v80, v100
	v_mul_f32_e32 v80, v81, v89
	v_mul_f32_e32 v84, v84, v92
	v_mul_f32_e32 v86, v86, v94
	v_mul_f32_e32 v89, v80, v101
	v_mul_f32_e32 v80, v82, v90
	v_mul_f32_e32 v84, v84, v96
	v_mul_f32_e32 v85, v85, v93
	v_mul_f32_e32 v86, v86, v98
	v_mul_f32_e32 v87, v87, v95
	v_mul_f32_e32 v90, v80, v102
	v_mul_f32_e32 v80, v83, v91
	v_mul_f32_e32 v85, v85, v97
	v_mul_f32_e32 v87, v87, v99
	v_mul_f32_e32 v83, v80, v103
	v_cvt_pk_bf16_f32 v80, v84, v85
	v_cvt_pk_bf16_f32 v81, v86, v87
	v_add_co_u32_e32 v84, vcc, s52, v116
	v_exp_f32_e64 v86, -v72
	s_nop 0
	v_addc_co_u32_e32 v85, vcc, 0, v117, vcc
	v_exp_f32_e64 v87, -v73
	v_cvt_pk_bf16_f32 v82, v88, v89
	v_cvt_pk_bf16_f32 v83, v90, v83
	global_store_dwordx4 v[84:85], v[80:83], off nt
	v_exp_f32_e64 v88, -v74
	v_exp_f32_e64 v89, -v75
	v_exp_f32_e64 v81, -v77
	v_exp_f32_e64 v80, -v76
	v_exp_f32_e64 v82, -v78
	v_exp_f32_e64 v83, -v79
	v_add_f32_e32 v86, 1.0, v86
	v_add_f32_e32 v87, 1.0, v87
	v_rcp_f32_e32 v86, v86
	v_add_f32_e32 v81, 1.0, v81
	v_add_f32_e32 v88, 1.0, v88
	v_rcp_f32_e32 v87, v87
	v_add_f32_e32 v80, 1.0, v80
	v_add_f32_e32 v82, 1.0, v82
	v_add_f32_e32 v89, 1.0, v89
	v_rcp_f32_e32 v81, v81
	v_rcp_f32_e32 v88, v88
	v_add_f32_e32 v83, 1.0, v83
	v_rcp_f32_e32 v80, v80
	v_rcp_f32_e32 v82, v82
	v_rcp_f32_e32 v89, v89
	v_mul_f32_e32 v64, v64, v72
	v_rcp_f32_e32 v83, v83
	v_mul_f32_e32 v72, v64, v86
	v_mul_f32_e32 v64, v65, v73
	v_mul_f32_e32 v69, v69, v77
	v_mul_f32_e32 v73, v64, v87
	v_mul_f32_e32 v64, v66, v74
	v_mul_f32_e32 v68, v68, v76
	v_mul_f32_e32 v69, v69, v81
	v_mul_f32_e32 v70, v70, v78
	v_mul_f32_e32 v74, v64, v88
	v_mul_f32_e32 v64, v67, v75
	v_mul_f32_e32 v68, v68, v80
	v_mul_f32_e32 v70, v70, v82
	v_mul_f32_e32 v71, v71, v79
	v_mul_f32_e32 v67, v64, v89
	v_cvt_pk_bf16_f32 v64, v68, v69
; __device__ __forceinline__ unsigned cvt_pk_bf16(float lo, float hi) { unsigned r; asm volatile("v_cvt_pk_bf16_f32 %0, %1, %2" : "=v"(r) : "v"(lo), "v"(hi)); return r; }
; #define PG8_BAR __builtin_amdgcn_s_barrier()
;     __device__ __forceinline__ void half(const f32x4 (&acc)[2][4][2], int pm, int ai, int pn, int wr, int wc, int fr, int fq) const {
;     ...
;             for (int m = 0; m < 4; ++m) {
;                 float a[8], e[8];
; #pragma unroll
;                 for (int q = 0; q < 8; ++q) a[q] = acc[0][m][q >> 2][q & 3];
; #pragma unroll
;                 for (int q = 0; q < 8; ++q) e[q] = __builtin_amdgcn_exp2f(-a[q]);
; #pragma unroll
;                 for (int q = 0; q < 8; ++q) e[q] += 1.f;
; #pragma unroll
;                 for (int q = 0; q < 8; ++q) e[q] = __builtin_amdgcn_rcpf(e[q]);
; #pragma unroll
;                 for (int q = 0; q < 8; ++q) a[q] = a[q] * acc[1][m][q >> 2][q & 3] * e[q];
;                 u32x4 w; w.x = cvt_pk_bf16(a[0], a[1]); w.y = cvt_pk_bf16(a[2], a[3]); w.z = cvt_pk_bf16(a[4], a[5]); w.w = cvt_pk_bf16(a[6], a[7]);
;                 const int row = row0 + ai * HALF + m * 16;
;                 bf16_t* dst = O + (((size_t)(row >> 8) * (ldc >> 6) + (col0 >> 6)) * 256 + (row & 255)) * 64 + (col0 & 63);
;                 if (wt) asm volatile("global_store_dwordx4 %0, %1, off sc1\n\ts_nop 1" :: "v"(dst), "v"(w) : "memory"); else *(u32x4*)dst = w; }
; template <class Epi, class Sched, bool ALIGN_EPI = false, bool SP2 = false>
; __device__ __forceinline__ void gemm_phase(PG8_LAS unsigned char* lds, const Gemm g, const Sched& S, const Epi& E) {
;     ...
;         if (!has_next) break;
; #pragma unroll
;         for (int a = 0; a < 2; ++a)
; #pragma unroll
;             for (int b = 0; b < 2; ++b)
; #pragma unroll
;                 for (int m = 0; m < 4; ++m)
; #pragma unroll
;                     for (int n = 0; n < 2; ++n) acc[a][b][m][n] = (f32x4){0.f, 0.f, 0.f, 0.f};
;         cur = nxt; cA = nA; cB = nB; ++ui;
;         if constexpr (ALIGN_EPI) { if (wr == 1) PG8_BAR; }
	v_exp_f32_e64 v69, -v56
	v_mul_f32_e32 v71, v71, v83
	v_cvt_pk_bf16_f32 v65, v70, v71
	v_exp_f32_e64 v70, -v57
	v_cvt_pk_bf16_f32 v66, v72, v73
	v_cvt_pk_bf16_f32 v67, v74, v67
	global_store_dwordx4 v[84:85], v[64:67], off offset:2048 nt
	v_exp_f32_e64 v71, -v58
	v_exp_f32_e64 v72, -v59
	v_exp_f32_e64 v65, -v60
	v_exp_f32_e64 v66, -v61
	v_add_f32_e32 v69, 1.0, v69
	v_add_f32_e32 v70, 1.0, v70
	v_rcp_f32_e32 v69, v69
	v_exp_f32_e64 v67, -v62
	v_add_f32_e32 v65, 1.0, v65
	v_add_f32_e32 v71, 1.0, v71
	v_rcp_f32_e32 v70, v70
	v_exp_f32_e64 v68, -v63
	v_add_f32_e32 v66, 1.0, v66
	v_add_f32_e32 v72, 1.0, v72
	v_rcp_f32_e32 v65, v65
	v_rcp_f32_e32 v71, v71
	v_rcp_f32_e32 v66, v66
	v_rcp_f32_e32 v72, v72
	v_mul_f32_e32 v48, v48, v56
	v_mul_f32_e32 v56, v48, v69
	v_mul_f32_e32 v48, v49, v57
	v_add_u32_e32 v64, s4, v151
	v_add_f32_e32 v67, 1.0, v67
	v_mul_f32_e32 v52, v52, v60
	v_mul_f32_e32 v57, v48, v70
	v_mul_f32_e32 v48, v50, v58
	v_lshrrev_b32_e32 v64, 8, v64
	v_add_f32_e32 v68, 1.0, v68
	v_rcp_f32_e32 v67, v67
	v_mul_f32_e32 v52, v52, v65
	v_mul_f32_e32 v53, v53, v61
	v_mul_f32_e32 v58, v48, v71
	v_mul_f32_e32 v48, v51, v59
	v_rcp_f32_e32 v68, v68
	v_mul_f32_e32 v53, v53, v66
	v_mul_f32_e32 v51, v48, v72
	v_cvt_pk_bf16_f32 v48, v52, v53
	v_mul_i32_i24_e32 v52, 0x58, v64
	v_ashrrev_i32_e32 v53, 31, v52
	v_mul_f32_e32 v54, v54, v62
	v_lshl_add_u64 v[52:53], v[52:53], 0, s[34:35]
	v_mul_f32_e32 v54, v54, v67
	v_mul_f32_e32 v55, v55, v63
	v_lshlrev_b64 v[52:53], 15, v[52:53]
	v_mul_f32_e32 v55, v55, v68
	v_cvt_pk_bf16_f32 v49, v54, v55
	v_lshl_add_u64 v[52:53], v[140:141], 0, v[52:53]
	v_exp_f32_e64 v54, -v40
	v_lshl_add_u64 v[52:53], v[52:53], 0, v[136:137]
	v_exp_f32_e64 v55, -v41
	v_cvt_pk_bf16_f32 v50, v56, v57
	v_cvt_pk_bf16_f32 v51, v58, v51
	global_store_dwordx4 v[52:53], v[48:51], off nt
	v_exp_f32_e64 v56, -v42
	v_exp_f32_e64 v57, -v43
	v_exp_f32_e64 v48, -v44
	v_exp_f32_e64 v49, -v45
	v_exp_f32_e64 v50, -v46
	v_exp_f32_e64 v51, -v47
	v_add_f32_e32 v54, 1.0, v54
	v_add_f32_e32 v55, 1.0, v55
	v_rcp_f32_e32 v54, v54
	v_add_f32_e32 v48, 1.0, v48
	v_add_f32_e32 v56, 1.0, v56
	v_rcp_f32_e32 v55, v55
	v_add_f32_e32 v49, 1.0, v49
	v_add_f32_e32 v57, 1.0, v57
	v_rcp_f32_e32 v48, v48
	v_rcp_f32_e32 v56, v56
	v_add_f32_e32 v50, 1.0, v50
	v_add_f32_e32 v51, 1.0, v51
	v_rcp_f32_e32 v49, v49
	v_rcp_f32_e32 v57, v57
	v_mul_f32_e32 v32, v32, v40
	v_rcp_f32_e32 v50, v50
	v_rcp_f32_e32 v51, v51
	v_mul_f32_e32 v40, v32, v54
	v_mul_f32_e32 v32, v33, v41
	v_mul_f32_e32 v36, v36, v44
	v_mul_f32_e32 v41, v32, v55
	v_mul_f32_e32 v32, v34, v42
	v_mul_f32_e32 v36, v36, v48
	v_mul_f32_e32 v37, v37, v45
	v_mul_f32_e32 v42, v32, v56
	v_mul_f32_e32 v32, v35, v43
	v_mul_f32_e32 v37, v37, v49
	v_mul_f32_e32 v38, v38, v46
	v_mul_f32_e32 v39, v39, v47
	v_mul_f32_e32 v35, v32, v57
	v_cvt_pk_bf16_f32 v32, v36, v37
	v_exp_f32_e64 v36, -v24
	v_mul_f32_e32 v38, v38, v50
	v_mul_f32_e32 v39, v39, v51
	v_cvt_pk_bf16_f32 v33, v38, v39
	v_cvt_pk_bf16_f32 v34, v40, v41
	v_exp_f32_e64 v37, -v25
	v_cvt_pk_bf16_f32 v35, v42, v35
	global_store_dwordx4 v[52:53], v[32:35], off offset:2048 nt
	v_exp_f32_e64 v38, -v26
	v_exp_f32_e64 v39, -v27
	v_exp_f32_e64 v34, -v30
	v_exp_f32_e64 v32, -v28
	v_exp_f32_e64 v33, -v29
	v_exp_f32_e64 v35, -v31
	v_add_f32_e32 v36, 1.0, v36
	v_add_f32_e32 v37, 1.0, v37
	v_rcp_f32_e32 v36, v36
	v_add_f32_e32 v34, 1.0, v34
	v_add_f32_e32 v38, 1.0, v38
	v_rcp_f32_e32 v37, v37
	v_add_f32_e32 v32, 1.0, v32
	v_add_f32_e32 v33, 1.0, v33
	v_add_f32_e32 v35, 1.0, v35
	v_add_f32_e32 v39, 1.0, v39
	v_rcp_f32_e32 v34, v34
	v_rcp_f32_e32 v38, v38
	v_rcp_f32_e32 v32, v32
	v_rcp_f32_e32 v33, v33
	v_rcp_f32_e32 v35, v35
	v_rcp_f32_e32 v39, v39
	v_mul_f32_e32 v16, v16, v24
	v_mul_f32_e32 v24, v16, v36
	v_mul_f32_e32 v16, v17, v25
	v_mul_f32_e32 v22, v22, v30
	v_mul_f32_e32 v25, v16, v37
	v_mul_f32_e32 v16, v18, v26
	v_mul_f32_e32 v20, v20, v28
	v_mul_f32_e32 v21, v21, v29
	v_mul_f32_e32 v22, v22, v34
	v_mul_f32_e32 v23, v23, v31
	v_mul_f32_e32 v26, v16, v38
	v_mul_f32_e32 v16, v19, v27
	v_mul_f32_e32 v20, v20, v32
	v_mul_f32_e32 v21, v21, v33
	v_mul_f32_e32 v23, v23, v35
	v_mul_f32_e32 v19, v16, v39
	v_cvt_pk_bf16_f32 v16, v20, v21
	v_cvt_pk_bf16_f32 v17, v22, v23
	v_exp_f32_e64 v22, -v8
	v_exp_f32_e64 v23, -v9
	v_cvt_pk_bf16_f32 v18, v24, v25
	v_add_co_u32_e32 v20, vcc, s52, v52
	v_exp_f32_e64 v24, -v10
	v_cvt_pk_bf16_f32 v19, v26, v19
	s_nop 0
	v_addc_co_u32_e32 v21, vcc, 0, v53, vcc
	v_exp_f32_e64 v25, -v11
	global_store_dwordx4 v[20:21], v[16:19], off nt
	v_add_f32_e32 v22, 1.0, v22
	v_add_f32_e32 v23, 1.0, v23
	v_exp_f32_e64 v16, -v12
	v_exp_f32_e64 v17, -v13
	v_exp_f32_e64 v18, -v14
	v_exp_f32_e64 v19, -v15
	v_rcp_f32_e32 v22, v22
	v_add_f32_e32 v24, 1.0, v24
	v_rcp_f32_e32 v23, v23
	v_add_f32_e32 v25, 1.0, v25
	v_rcp_f32_e32 v24, v24
	v_add_f32_e32 v16, 1.0, v16
	v_add_f32_e32 v17, 1.0, v17
	v_add_f32_e32 v18, 1.0, v18
	v_add_f32_e32 v19, 1.0, v19
	v_rcp_f32_e32 v25, v25
	v_mul_f32_e32 v0, v0, v8
	v_rcp_f32_e32 v16, v16
	v_rcp_f32_e32 v17, v17
	v_rcp_f32_e32 v18, v18
	v_rcp_f32_e32 v19, v19
	v_mul_f32_e32 v8, v0, v22
	v_mul_f32_e32 v0, v1, v9
	v_mul_f32_e32 v9, v0, v23
	v_mul_f32_e32 v0, v2, v10
	v_mul_f32_e32 v10, v0, v24
	v_mul_f32_e32 v0, v3, v11
	v_mul_f32_e32 v4, v4, v12
	v_mul_f32_e32 v5, v5, v13
	v_mul_f32_e32 v6, v6, v14
	v_mul_f32_e32 v7, v7, v15
	v_mul_f32_e32 v3, v0, v25
	s_andn2_b64 vcc, exec, s[36:37]
	s_mov_b64 s[4:5], -1
	v_mul_f32_e32 v4, v4, v16
	v_mul_f32_e32 v5, v5, v17
	v_mul_f32_e32 v6, v6, v18
	v_mul_f32_e32 v7, v7, v19
	v_cvt_pk_bf16_f32 v0, v4, v5
	v_cvt_pk_bf16_f32 v1, v6, v7
	v_cvt_pk_bf16_f32 v2, v8, v9
	v_cvt_pk_bf16_f32 v3, v10, v3
	global_store_dwordx4 v[20:21], v[0:3], off offset:2048 nt
	s_cbranch_vccnz .LBB0_3050
	s_andn2_b64 vcc, exec, s[0:1]
	s_cbranch_vccnz .LBB0_3049
	s_barrier
	s_branch .LBB0_3049
